# RG-LRU gate loops (8 loops): the 16 xc-fragment LDS reads per s-step run ahead of the MFMAs in a ring of unused VGPR quads
# speedup vs baseline: 1.0019x; 1.0006x over previous
; #define LAS __attribute__((address_space(3)))
; template <bool PASS2>
; __device__ __forceinline__ void lru_item(const Frame& F, const Args& a, int item) {
;     ...
;             f32x4 ar[4], ai[4], ax[4];
; #pragma unroll
;             for (int rt = 0; rt < 4; ++rt) { ar[rt] = (f32x4){0.f, 0.f, 0.f, 0.f}; ai[rt] = (f32x4){0.f, 0.f, 0.f, 0.f}; ax[rt] = (f32x4){0.f, 0.f, 0.f, 0.f};
; #pragma unroll
;                 for (int ks = 0; ks < 4; ++ks) { const bf16x8 xf = *(const LAS bf16x8*)(AT + (64 * s + 16 * rt + fr) * AT_PITCH + 64 * ks + 16 * fq);
;                     ar[rt] = __builtin_amdgcn_mfma_f32_16x16x32_bf16(xf, wrf[ks], ar[rt], 0, 0, 0); ai[rt] = __builtin_amdgcn_mfma_f32_16x16x32_bf16(xf, wif[ks], ai[rt], 0, 0, 0);
;                     if (ks == ks0) ax[rt] = __builtin_amdgcn_mfma_f32_16x16x32_bf16(xf, sel, ax[rt], 0, 0, 0); } }
.LBB0_150:
	v_add_u32_e32 v107, v132, v93
	v_add_u32_e32 v193, 0x11400, v107
	ds_read_b128 v[194:197], v193
	ds_read_b128 v[198:201], v193 offset:64
	ds_read_b128 v[202:205], v193 offset:128
	ds_read_b128 v[206:209], v193 offset:192
	ds_read_b128 v[210:213], v193 offset:4352
	ds_read_b128 v[214:217], v193 offset:4416
	ds_read_b128 v[218:221], v193 offset:4480
	ds_read_b128 v[222:225], v193 offset:4544
	ds_read_b128 v[226:229], v193 offset:8704
	ds_read_b128 v[248:251], v193 offset:8768
	ds_read_b128 v[252:255], v193 offset:8832
	v_cndmask_b32_e64 v40, 0, 1, s[2:3]
	v_cmp_ne_u32_e64 s[10:11], 1, v40
	s_mov_b32 s14, s12
	s_mov_b32 s15, s12
	s_mov_b32 s13, s12
	v_mov_b64_e32 v[66:67], s[14:15]
	v_mov_b64_e32 v[64:65], s[12:13]
	s_andn2_b64 vcc, exec, s[2:3]
	s_waitcnt vmcnt(9) lgkmcnt(10)
	v_mfma_f32_16x16x32_bf16 v[44:47], v[194:197], v[4:7], 0
	s_waitcnt vmcnt(3)
	v_mfma_f32_16x16x32_bf16 v[40:43], v[194:197], v[20:23], 0
	s_cbranch_vccnz .LBB0_152
	v_mfma_f32_16x16x32_bf16 v[64:67], v[194:197], v[0:3], 0
.LBB0_152:
	ds_read_b128 v[194:197], v193 offset:8896
	s_andn2_b64 vcc, exec, s[16:17]
	s_waitcnt lgkmcnt(10)
	v_mfma_f32_16x16x32_bf16 v[36:39], v[198:201], v[8:11], v[44:47]
	s_nop 2
	v_cndmask_b32_e64 v44, 0, 1, s[16:17]
	v_cmp_ne_u32_e64 s[4:5], 1, v44
	s_waitcnt vmcnt(2)
	v_mfma_f32_16x16x32_bf16 v[40:43], v[198:201], v[24:27], v[40:43]
	s_cbranch_vccnz .LBB0_154
	v_mfma_f32_16x16x32_bf16 v[64:67], v[198:201], v[0:3], v[64:67]
.LBB0_154:
	ds_read_b128 v[198:201], v193 offset:13056
	v_cndmask_b32_e64 v48, 0, 1, s[18:19]
	v_cmp_ne_u32_e64 s[6:7], 1, v48
	s_andn2_b64 vcc, exec, s[18:19]
	s_waitcnt lgkmcnt(10)
	v_mfma_f32_16x16x32_bf16 v[36:39], v[202:205], v[12:15], v[36:39]
	s_waitcnt vmcnt(1)
	v_mfma_f32_16x16x32_bf16 v[40:43], v[202:205], v[28:31], v[40:43]
	s_cbranch_vccnz .LBB0_156
	v_mfma_f32_16x16x32_bf16 v[64:67], v[202:205], v[0:3], v[64:67]
.LBB0_156:
	ds_read_b128 v[202:205], v193 offset:13120
	s_andn2_b64 vcc, exec, s[28:29]
	s_waitcnt lgkmcnt(10)
	v_mfma_f32_16x16x32_bf16 v[80:83], v[206:209], v[16:19], v[36:39]
	s_nop 2
	v_cndmask_b32_e64 v36, 0, 1, s[28:29]
	v_cmp_ne_u32_e64 s[8:9], 1, v36
	s_waitcnt vmcnt(0)
	v_mfma_f32_16x16x32_bf16 v[76:79], v[206:209], v[32:35], v[40:43]
	s_cbranch_vccnz .LBB0_158
	v_mfma_f32_16x16x32_bf16 v[64:67], v[206:209], v[0:3], v[64:67]
.LBB0_158:
	ds_read_b128 v[206:209], v193 offset:13184
	s_mov_b32 s14, s12
	s_mov_b32 s15, s12
	s_mov_b32 s13, s12
	v_mov_b64_e32 v[54:55], s[14:15]
	s_and_b64 vcc, exec, s[10:11]
	v_mov_b64_e32 v[52:53], s[12:13]
	s_waitcnt lgkmcnt(10)
	v_mfma_f32_16x16x32_bf16 v[40:43], v[210:213], v[4:7], 0
	v_mfma_f32_16x16x32_bf16 v[44:47], v[210:213], v[20:23], 0
	s_cbranch_vccnz .LBB0_160
	v_mfma_f32_16x16x32_bf16 v[52:55], v[210:213], v[0:3], 0
.LBB0_160:
	ds_read_b128 v[210:213], v193 offset:13248
	s_and_b64 vcc, exec, s[4:5]
	s_waitcnt lgkmcnt(10)
	v_mfma_f32_16x16x32_bf16 v[36:39], v[214:217], v[8:11], v[40:43]
	v_mfma_f32_16x16x32_bf16 v[40:43], v[214:217], v[24:27], v[44:47]
	s_cbranch_vccnz .LBB0_162
	v_mfma_f32_16x16x32_bf16 v[52:55], v[214:217], v[0:3], v[52:55]
.LBB0_162:
	s_nop 0
	s_and_b64 vcc, exec, s[6:7]
	s_waitcnt lgkmcnt(9)
	v_mfma_f32_16x16x32_bf16 v[36:39], v[218:221], v[12:15], v[36:39]
	v_mfma_f32_16x16x32_bf16 v[40:43], v[218:221], v[28:31], v[40:43]
	s_cbranch_vccnz .LBB0_164
	v_mfma_f32_16x16x32_bf16 v[52:55], v[218:221], v[0:3], v[52:55]
.LBB0_164:
	s_and_b64 vcc, exec, s[8:9]
	s_waitcnt lgkmcnt(8)
	v_mfma_f32_16x16x32_bf16 v[72:75], v[222:225], v[16:19], v[36:39]
	v_mfma_f32_16x16x32_bf16 v[68:71], v[222:225], v[32:35], v[40:43]
	s_cbranch_vccnz .LBB0_166
	v_mfma_f32_16x16x32_bf16 v[52:55], v[222:225], v[0:3], v[52:55]
.LBB0_166:
	s_mov_b32 s14, s12
	s_mov_b32 s15, s12
	s_mov_b32 s13, s12
	v_mov_b64_e32 v[42:43], s[14:15]
	s_and_b64 vcc, exec, s[10:11]
	v_mov_b64_e32 v[40:41], s[12:13]
	s_waitcnt lgkmcnt(7)
	v_mfma_f32_16x16x32_bf16 v[44:47], v[226:229], v[4:7], 0
	v_mfma_f32_16x16x32_bf16 v[48:51], v[226:229], v[20:23], 0
	s_cbranch_vccnz .LBB0_168
	v_mfma_f32_16x16x32_bf16 v[40:43], v[226:229], v[0:3], 0
.LBB0_168:
	s_and_b64 vcc, exec, s[4:5]
	s_waitcnt lgkmcnt(6)
	v_mfma_f32_16x16x32_bf16 v[36:39], v[248:251], v[8:11], v[44:47]
	v_mfma_f32_16x16x32_bf16 v[44:47], v[248:251], v[24:27], v[48:51]
	s_cbranch_vccnz .LBB0_170
	v_mfma_f32_16x16x32_bf16 v[40:43], v[248:251], v[0:3], v[40:43]
.LBB0_170:
	s_nop 0
	s_and_b64 vcc, exec, s[6:7]
	s_waitcnt lgkmcnt(5)
	v_mfma_f32_16x16x32_bf16 v[36:39], v[252:255], v[12:15], v[36:39]
	v_mfma_f32_16x16x32_bf16 v[44:47], v[252:255], v[28:31], v[44:47]
	s_cbranch_vccnz .LBB0_172
	v_mfma_f32_16x16x32_bf16 v[40:43], v[252:255], v[0:3], v[40:43]
.LBB0_172:
	s_and_b64 vcc, exec, s[8:9]
	s_waitcnt lgkmcnt(4)
	v_mfma_f32_16x16x32_bf16 v[60:63], v[194:197], v[16:19], v[36:39]
	v_mfma_f32_16x16x32_bf16 v[56:59], v[194:197], v[32:35], v[44:47]
	s_cbranch_vccnz .LBB0_174
	v_mfma_f32_16x16x32_bf16 v[40:43], v[194:197], v[0:3], v[40:43]
.LBB0_174:
	s_mov_b32 s14, s12
	s_mov_b32 s15, s12
	s_mov_b32 s13, s12
	v_mov_b64_e32 v[38:39], s[14:15]
	s_and_b64 vcc, exec, s[10:11]
	v_mov_b64_e32 v[36:37], s[12:13]
	s_waitcnt lgkmcnt(3)
	v_mfma_f32_16x16x32_bf16 v[48:51], v[198:201], v[4:7], 0
	v_mfma_f32_16x16x32_bf16 v[84:87], v[198:201], v[20:23], 0
	s_cbranch_vccnz .LBB0_176
	v_mfma_f32_16x16x32_bf16 v[36:39], v[198:201], v[0:3], 0
.LBB0_176:
	s_and_b64 vcc, exec, s[4:5]
	s_waitcnt lgkmcnt(2)
	v_mfma_f32_16x16x32_bf16 v[44:47], v[202:205], v[8:11], v[48:51]
	v_mfma_f32_16x16x32_bf16 v[48:51], v[202:205], v[24:27], v[84:87]
	s_cbranch_vccnz .LBB0_178
	v_mfma_f32_16x16x32_bf16 v[36:39], v[202:205], v[0:3], v[36:39]
.LBB0_178:
	s_nop 0
	s_and_b64 vcc, exec, s[6:7]
	s_waitcnt lgkmcnt(1)
	v_mfma_f32_16x16x32_bf16 v[44:47], v[206:209], v[12:15], v[44:47]
	v_mfma_f32_16x16x32_bf16 v[84:87], v[206:209], v[28:31], v[48:51]
	s_cbranch_vccnz .LBB0_180
	v_mfma_f32_16x16x32_bf16 v[36:39], v[206:209], v[0:3], v[36:39]
.LBB0_180:
	s_nop 0
	s_and_b64 vcc, exec, s[8:9]
	s_waitcnt lgkmcnt(0)
	v_mfma_f32_16x16x32_bf16 v[48:51], v[210:213], v[16:19], v[44:47]
	v_mfma_f32_16x16x32_bf16 v[44:47], v[210:213], v[32:35], v[84:87]
	s_cbranch_vccnz .LBB0_182
	v_mfma_f32_16x16x32_bf16 v[36:39], v[210:213], v[0:3], v[36:39]

; #define LAS __attribute__((address_space(3)))
; template <bool PASS2>
; __device__ __forceinline__ void lru_item(const Frame& F, const Args& a, int item) {
;     ...
;             f32x4 ar[4], ai[4], ax[4];
; #pragma unroll
;             for (int rt = 0; rt < 4; ++rt) { ar[rt] = (f32x4){0.f, 0.f, 0.f, 0.f}; ai[rt] = (f32x4){0.f, 0.f, 0.f, 0.f}; ax[rt] = (f32x4){0.f, 0.f, 0.f, 0.f};
; #pragma unroll
;                 for (int ks = 0; ks < 4; ++ks) { const bf16x8 xf = *(const LAS bf16x8*)(AT + (64 * s + 16 * rt + fr) * AT_PITCH + 64 * ks + 16 * fq);
;                     ar[rt] = __builtin_amdgcn_mfma_f32_16x16x32_bf16(xf, wrf[ks], ar[rt], 0, 0, 0); ai[rt] = __builtin_amdgcn_mfma_f32_16x16x32_bf16(xf, wif[ks], ai[rt], 0, 0, 0);
;                     if (ks == ks0) ax[rt] = __builtin_amdgcn_mfma_f32_16x16x32_bf16(xf, sel, ax[rt], 0, 0, 0); } }
.LBB0_187:
	v_bitop3_b32 v36, s39, v101, v123 bitop3:0xde
	v_mul_lo_u32 v36, v36, s45
	v_add_u32_e32 v107, v110, v36
	ds_read_b128 v[194:197], v107
	ds_read_b128 v[198:201], v107 offset:64
	ds_read_b128 v[202:205], v107 offset:128
	ds_read_b128 v[206:209], v107 offset:192
	ds_read_b128 v[210:213], v107 offset:4352
	ds_read_b128 v[214:217], v107 offset:4416
	ds_read_b128 v[218:221], v107 offset:4480
	ds_read_b128 v[222:225], v107 offset:4544
	ds_read_b128 v[226:229], v107 offset:8704
	ds_read_b128 v[248:251], v107 offset:8768
	ds_read_b128 v[252:255], v107 offset:8832
	s_mov_b32 s14, s12
	s_mov_b32 s15, s12
	s_mov_b32 s13, s12
	v_mov_b64_e32 v[38:39], s[14:15]
	s_and_b64 vcc, exec, s[10:11]
	v_mov_b64_e32 v[36:37], s[12:13]
	s_waitcnt vmcnt(9) lgkmcnt(10)
	v_mfma_f32_16x16x32_bf16 v[44:47], v[194:197], v[4:7], 0
	s_waitcnt vmcnt(3)
	v_mfma_f32_16x16x32_bf16 v[48:51], v[194:197], v[20:23], 0
	s_cbranch_vccnz .LBB0_189
	v_mfma_f32_16x16x32_bf16 v[36:39], v[194:197], v[0:3], 0
.LBB0_189:
	ds_read_b128 v[194:197], v107 offset:8896
	s_and_b64 vcc, exec, s[4:5]
	s_waitcnt lgkmcnt(10)
	v_mfma_f32_16x16x32_bf16 v[40:43], v[198:201], v[8:11], v[44:47]
	s_waitcnt vmcnt(2)
	v_mfma_f32_16x16x32_bf16 v[44:47], v[198:201], v[24:27], v[48:51]
	s_cbranch_vccnz .LBB0_191
	v_mfma_f32_16x16x32_bf16 v[36:39], v[198:201], v[0:3], v[36:39]
.LBB0_191:
	ds_read_b128 v[198:201], v107 offset:13056
	s_and_b64 vcc, exec, s[6:7]
	s_waitcnt lgkmcnt(10)
	v_mfma_f32_16x16x32_bf16 v[40:43], v[202:205], v[12:15], v[40:43]
	s_waitcnt vmcnt(1)
	v_mfma_f32_16x16x32_bf16 v[48:51], v[202:205], v[28:31], v[44:47]
	s_cbranch_vccnz .LBB0_193
	v_mfma_f32_16x16x32_bf16 v[36:39], v[202:205], v[0:3], v[36:39]
.LBB0_193:
	ds_read_b128 v[202:205], v107 offset:13120
	s_and_b64 vcc, exec, s[8:9]
	s_waitcnt lgkmcnt(10)
	v_mfma_f32_16x16x32_bf16 v[44:47], v[206:209], v[16:19], v[40:43]
	s_waitcnt vmcnt(0)
	v_mfma_f32_16x16x32_bf16 v[40:43], v[206:209], v[32:35], v[48:51]
	s_cbranch_vccnz .LBB0_195
	v_mfma_f32_16x16x32_bf16 v[36:39], v[206:209], v[0:3], v[36:39]
.LBB0_195:
	ds_read_b128 v[206:209], v107 offset:13184
	s_mov_b32 s14, s12
	s_mov_b32 s15, s12
	s_mov_b32 s13, s12
	v_mov_b64_e32 v[50:51], s[14:15]
	s_and_b64 vcc, exec, s[10:11]
	v_mov_b64_e32 v[48:49], s[12:13]
	s_waitcnt lgkmcnt(10)
	v_mfma_f32_16x16x32_bf16 v[56:59], v[210:213], v[4:7], 0
	v_mfma_f32_16x16x32_bf16 v[60:63], v[210:213], v[20:23], 0
	s_cbranch_vccnz .LBB0_197
	v_mfma_f32_16x16x32_bf16 v[48:51], v[210:213], v[0:3], 0
.LBB0_197:
	ds_read_b128 v[210:213], v107 offset:13248
	s_and_b64 vcc, exec, s[4:5]
	s_waitcnt lgkmcnt(10)
	s_nop 0
	v_mfma_f32_16x16x32_bf16 v[52:55], v[214:217], v[8:11], v[56:59]
	v_mfma_f32_16x16x32_bf16 v[56:59], v[214:217], v[24:27], v[60:63]
	s_cbranch_vccnz .LBB0_199
	v_mfma_f32_16x16x32_bf16 v[48:51], v[214:217], v[0:3], v[48:51]
.LBB0_199:
	s_and_b64 vcc, exec, s[6:7]
	s_waitcnt lgkmcnt(9)
	v_mfma_f32_16x16x32_bf16 v[52:55], v[218:221], v[12:15], v[52:55]
	v_mfma_f32_16x16x32_bf16 v[60:63], v[218:221], v[28:31], v[56:59]
	s_cbranch_vccnz .LBB0_201
	v_mfma_f32_16x16x32_bf16 v[48:51], v[218:221], v[0:3], v[48:51]
.LBB0_201:
	s_and_b64 vcc, exec, s[8:9]
	s_waitcnt lgkmcnt(8)
	v_mfma_f32_16x16x32_bf16 v[56:59], v[222:225], v[16:19], v[52:55]
	v_mfma_f32_16x16x32_bf16 v[52:55], v[222:225], v[32:35], v[60:63]
	s_cbranch_vccnz .LBB0_203
	v_mfma_f32_16x16x32_bf16 v[48:51], v[222:225], v[0:3], v[48:51]
.LBB0_203:
	s_mov_b32 s14, s12
	s_mov_b32 s15, s12
	s_mov_b32 s13, s12
	v_mov_b64_e32 v[62:63], s[14:15]
	s_and_b64 vcc, exec, s[10:11]
	v_mov_b64_e32 v[60:61], s[12:13]
	s_waitcnt lgkmcnt(7)
	v_mfma_f32_16x16x32_bf16 v[68:71], v[226:229], v[4:7], 0
	v_mfma_f32_16x16x32_bf16 v[72:75], v[226:229], v[20:23], 0
	s_cbranch_vccnz .LBB0_205
	v_mfma_f32_16x16x32_bf16 v[60:63], v[226:229], v[0:3], 0
.LBB0_205:
	s_and_b64 vcc, exec, s[4:5]
	s_waitcnt lgkmcnt(6)
	s_nop 0
	v_mfma_f32_16x16x32_bf16 v[64:67], v[248:251], v[8:11], v[68:71]
	v_mfma_f32_16x16x32_bf16 v[68:71], v[248:251], v[24:27], v[72:75]
	s_cbranch_vccnz .LBB0_207
	v_mfma_f32_16x16x32_bf16 v[60:63], v[248:251], v[0:3], v[60:63]
.LBB0_207:
	s_and_b64 vcc, exec, s[6:7]
	s_waitcnt lgkmcnt(5)
	v_mfma_f32_16x16x32_bf16 v[64:67], v[252:255], v[12:15], v[64:67]
	v_mfma_f32_16x16x32_bf16 v[72:75], v[252:255], v[28:31], v[68:71]
	s_cbranch_vccnz .LBB0_209
	v_mfma_f32_16x16x32_bf16 v[60:63], v[252:255], v[0:3], v[60:63]
.LBB0_209:
	s_and_b64 vcc, exec, s[8:9]
	s_waitcnt lgkmcnt(4)
	v_mfma_f32_16x16x32_bf16 v[68:71], v[194:197], v[16:19], v[64:67]
	v_mfma_f32_16x16x32_bf16 v[64:67], v[194:197], v[32:35], v[72:75]
	s_cbranch_vccnz .LBB0_211
	v_mfma_f32_16x16x32_bf16 v[60:63], v[194:197], v[0:3], v[60:63]
.LBB0_211:
	s_mov_b32 s14, s12
	s_mov_b32 s15, s12
	s_mov_b32 s13, s12
	v_mov_b64_e32 v[74:75], s[14:15]
	s_and_b64 vcc, exec, s[10:11]
	v_mov_b64_e32 v[72:73], s[12:13]
	s_waitcnt lgkmcnt(3)
	v_mfma_f32_16x16x32_bf16 v[80:83], v[198:201], v[4:7], 0
	v_mfma_f32_16x16x32_bf16 v[84:87], v[198:201], v[20:23], 0
	s_cbranch_vccnz .LBB0_213
	v_mfma_f32_16x16x32_bf16 v[72:75], v[198:201], v[0:3], 0
.LBB0_213:
	s_and_b64 vcc, exec, s[4:5]
	s_waitcnt lgkmcnt(2)
	s_nop 0
	v_mfma_f32_16x16x32_bf16 v[76:79], v[202:205], v[8:11], v[80:83]
	v_mfma_f32_16x16x32_bf16 v[80:83], v[202:205], v[24:27], v[84:87]
	s_cbranch_vccnz .LBB0_215
	v_mfma_f32_16x16x32_bf16 v[72:75], v[202:205], v[0:3], v[72:75]
.LBB0_215:
	s_and_b64 vcc, exec, s[6:7]
	s_waitcnt lgkmcnt(1)
	v_mfma_f32_16x16x32_bf16 v[76:79], v[206:209], v[12:15], v[76:79]
	v_mfma_f32_16x16x32_bf16 v[84:87], v[206:209], v[28:31], v[80:83]
	s_cbranch_vccnz .LBB0_217
	v_mfma_f32_16x16x32_bf16 v[72:75], v[206:209], v[0:3], v[72:75]
.LBB0_217:
	s_and_b64 vcc, exec, s[8:9]
	s_waitcnt lgkmcnt(0)
	v_mfma_f32_16x16x32_bf16 v[80:83], v[210:213], v[16:19], v[76:79]
	v_mfma_f32_16x16x32_bf16 v[76:79], v[210:213], v[32:35], v[84:87]
	s_cbranch_vccnz .LBB0_219
	v_mfma_f32_16x16x32_bf16 v[72:75], v[210:213], v[0:3], v[72:75]

; #define LAS __attribute__((address_space(3)))
; template <bool PASS2>
; __device__ __forceinline__ void lru_item(const Frame& F, const Args& a, int item) {
;     ...
;             f32x4 ar[4], ai[4], ax[4];
; #pragma unroll
;             for (int rt = 0; rt < 4; ++rt) { ar[rt] = (f32x4){0.f, 0.f, 0.f, 0.f}; ai[rt] = (f32x4){0.f, 0.f, 0.f, 0.f}; ax[rt] = (f32x4){0.f, 0.f, 0.f, 0.f};
; #pragma unroll
;                 for (int ks = 0; ks < 4; ++ks) { const bf16x8 xf = *(const LAS bf16x8*)(AT + (64 * s + 16 * rt + fr) * AT_PITCH + 64 * ks + 16 * fq);
;                     ar[rt] = __builtin_amdgcn_mfma_f32_16x16x32_bf16(xf, wrf[ks], ar[rt], 0, 0, 0); ai[rt] = __builtin_amdgcn_mfma_f32_16x16x32_bf16(xf, wif[ks], ai[rt], 0, 0, 0);
;                     if (ks == ks0) ax[rt] = __builtin_amdgcn_mfma_f32_16x16x32_bf16(xf, sel, ax[rt], 0, 0, 0); } }
.LBB0_708:
	v_add_u32_e32 v125, v209, v105
	v_add_u32_e32 v240, 0x11400, v125
	ds_read_b128 v[212:215], v240
	ds_read_b128 v[216:219], v240 offset:64
	ds_read_b128 v[220:223], v240 offset:128
	ds_read_b128 v[224:227], v240 offset:192
	ds_read_b128 v[228:231], v240 offset:4352
	ds_read_b128 v[232:235], v240 offset:4416
	ds_read_b128 v[236:239], v240 offset:4480
	ds_read_b128 v[244:247], v240 offset:4544
	ds_read_b128 v[248:251], v240 offset:8704
	ds_read_b128 v[252:255], v240 offset:8768
	v_mov_b32_e32 v182, v4
	v_mov_b32_e32 v179, v7
	v_mov_b32_e32 v180, v6
	v_mov_b32_e32 v181, v5
	v_mov_b32_e32 v174, v12
	v_cndmask_b32_e64 v12, 0, 1, s[36:37]
	v_mov_b32_e32 v173, v13
	v_mov_b32_e32 v175, v11
	v_mov_b32_e32 v176, v10
	v_mov_b32_e32 v177, v9
	v_mov_b32_e32 v178, v8
	s_waitcnt lgkmcnt(9)
	v_mfma_f32_16x16x32_bf16 v[8:11], v[212:215], v[36:39], 0
	v_cmp_ne_u32_e64 s[8:9], 1, v12
	s_mov_b32 s29, s28
	s_mov_b32 s30, s28
	v_mfma_f32_16x16x32_bf16 v[12:15], v[212:215], v[44:47], 0
	s_mov_b32 s31, s28
	v_mov_b64_e32 v[28:29], s[28:29]
	v_mov_b32_e32 v183, v132
	v_mov_b32_e32 v184, v131
	v_mov_b32_e32 v185, v146
	v_mov_b32_e32 v186, v145
	v_mov_b32_e32 v187, v143
	v_mov_b32_e32 v188, v133
	v_mov_b32_e32 v132, v198
	v_mov_b32_e32 v131, v200
	v_mov_b32_e32 v146, v202
	v_mov_b32_e32 v145, v203
	v_mov_b32_e32 v143, v205
	v_mov_b32_e32 v133, v124
	v_mov_b64_e32 v[30:31], s[30:31]
	s_andn2_b64 vcc, exec, s[36:37]
	s_cbranch_vccnz .LBB0_710
	v_mfma_f32_16x16x32_bf16 v[28:31], v[212:215], v[0:3], 0
.LBB0_710:
	ds_read_b128 v[212:215], v240 offset:8832
	s_andn2_b64 vcc, exec, s[38:39]
	s_waitcnt lgkmcnt(9)
	v_mfma_f32_16x16x32_bf16 v[4:7], v[216:219], v[40:43], v[8:11]
	s_nop 2
	v_cndmask_b32_e64 v8, 0, 1, s[38:39]
	v_cmp_ne_u32_e64 s[10:11], 1, v8
	v_mfma_f32_16x16x32_bf16 v[8:11], v[216:219], v[48:51], v[12:15]
	s_cbranch_vccnz .LBB0_712
	v_mfma_f32_16x16x32_bf16 v[28:31], v[216:219], v[0:3], v[28:31]
.LBB0_712:
	s_nop 0
	ds_read_b128 v[216:219], v240 offset:8896
	v_cndmask_b32_e64 v16, 0, 1, s[40:41]
	v_cmp_ne_u32_e64 s[12:13], 1, v16
	s_andn2_b64 vcc, exec, s[40:41]
	s_waitcnt lgkmcnt(9)
	v_mfma_f32_16x16x32_bf16 v[4:7], v[220:223], v[52:55], v[4:7]
	v_mfma_f32_16x16x32_bf16 v[8:11], v[220:223], v[60:63], v[8:11]
	s_cbranch_vccnz .LBB0_714
	v_mfma_f32_16x16x32_bf16 v[28:31], v[220:223], v[0:3], v[28:31]
.LBB0_714:
	ds_read_b128 v[220:223], v240 offset:13056
	s_andn2_b64 vcc, exec, s[42:43]
	s_waitcnt lgkmcnt(9)
	v_mfma_f32_16x16x32_bf16 v[80:83], v[224:227], v[56:59], v[4:7]
	s_nop 2
	v_cndmask_b32_e64 v4, 0, 1, s[42:43]
	v_cmp_ne_u32_e64 s[14:15], 1, v4
	v_mfma_f32_16x16x32_bf16 v[76:79], v[224:227], v[64:67], v[8:11]
	s_cbranch_vccnz .LBB0_716
	v_mfma_f32_16x16x32_bf16 v[28:31], v[224:227], v[0:3], v[28:31]
.LBB0_716:
	ds_read_b128 v[224:227], v240 offset:13120
	s_mov_b32 s29, s28
	s_mov_b32 s30, s28
	s_mov_b32 s31, s28
	v_mov_b64_e32 v[20:21], s[28:29]
	s_and_b64 vcc, exec, s[8:9]
	v_mov_b64_e32 v[22:23], s[30:31]
	s_waitcnt lgkmcnt(9)
	v_mfma_f32_16x16x32_bf16 v[8:11], v[228:231], v[36:39], 0
	v_mfma_f32_16x16x32_bf16 v[12:15], v[228:231], v[44:47], 0
	s_cbranch_vccnz .LBB0_718
	v_mfma_f32_16x16x32_bf16 v[20:23], v[228:231], v[0:3], 0
.LBB0_718:
	ds_read_b128 v[228:231], v240 offset:13184
	s_and_b64 vcc, exec, s[10:11]
	s_waitcnt lgkmcnt(9)
	v_mfma_f32_16x16x32_bf16 v[4:7], v[232:235], v[40:43], v[8:11]
	v_mfma_f32_16x16x32_bf16 v[8:11], v[232:235], v[48:51], v[12:15]
	s_cbranch_vccnz .LBB0_720
	v_mfma_f32_16x16x32_bf16 v[20:23], v[232:235], v[0:3], v[20:23]
.LBB0_720:
	s_nop 0
	ds_read_b128 v[232:235], v240 offset:13248
	s_and_b64 vcc, exec, s[12:13]
	s_waitcnt lgkmcnt(9)
	v_mfma_f32_16x16x32_bf16 v[4:7], v[236:239], v[52:55], v[4:7]
	v_mfma_f32_16x16x32_bf16 v[8:11], v[236:239], v[60:63], v[8:11]
	s_cbranch_vccnz .LBB0_722
	v_mfma_f32_16x16x32_bf16 v[20:23], v[236:239], v[0:3], v[20:23]
.LBB0_722:
	s_and_b64 vcc, exec, s[14:15]
	s_waitcnt lgkmcnt(8)
	v_mfma_f32_16x16x32_bf16 v[72:75], v[244:247], v[56:59], v[4:7]
	v_mfma_f32_16x16x32_bf16 v[68:71], v[244:247], v[64:67], v[8:11]
	s_cbranch_vccnz .LBB0_724
	v_mfma_f32_16x16x32_bf16 v[20:23], v[244:247], v[0:3], v[20:23]
.LBB0_724:
	s_mov_b32 s29, s28
	s_mov_b32 s30, s28
	s_mov_b32 s31, s28
	v_mov_b64_e32 v[8:9], s[28:29]
	s_and_b64 vcc, exec, s[8:9]
	v_mov_b64_e32 v[10:11], s[30:31]
	s_waitcnt lgkmcnt(7)
	v_mfma_f32_16x16x32_bf16 v[12:15], v[248:251], v[36:39], 0
	v_mfma_f32_16x16x32_bf16 v[16:19], v[248:251], v[44:47], 0
	s_cbranch_vccnz .LBB0_726
	v_mfma_f32_16x16x32_bf16 v[8:11], v[248:251], v[0:3], 0
.LBB0_726:
	s_and_b64 vcc, exec, s[10:11]
	s_waitcnt lgkmcnt(6)
	v_mfma_f32_16x16x32_bf16 v[4:7], v[252:255], v[40:43], v[12:15]
	v_mfma_f32_16x16x32_bf16 v[12:15], v[252:255], v[48:51], v[16:19]
	s_cbranch_vccnz .LBB0_728
	v_mfma_f32_16x16x32_bf16 v[8:11], v[252:255], v[0:3], v[8:11]
.LBB0_728:
	s_nop 0
	s_and_b64 vcc, exec, s[12:13]
	s_waitcnt lgkmcnt(5)
	v_mfma_f32_16x16x32_bf16 v[4:7], v[212:215], v[52:55], v[4:7]
	v_mfma_f32_16x16x32_bf16 v[12:15], v[212:215], v[60:63], v[12:15]
	s_cbranch_vccnz .LBB0_730
	v_mfma_f32_16x16x32_bf16 v[8:11], v[212:215], v[0:3], v[8:11]
.LBB0_730:
	s_and_b64 vcc, exec, s[14:15]
	s_waitcnt lgkmcnt(4)
	v_mfma_f32_16x16x32_bf16 v[32:35], v[216:219], v[56:59], v[4:7]
	v_mfma_f32_16x16x32_bf16 v[24:27], v[216:219], v[64:67], v[12:15]
	s_cbranch_vccnz .LBB0_732
	v_mfma_f32_16x16x32_bf16 v[8:11], v[216:219], v[0:3], v[8:11]
.LBB0_732:
	s_mov_b32 s29, s28
	s_mov_b32 s30, s28
	s_mov_b32 s31, s28
	v_mov_b64_e32 v[4:5], s[28:29]
	s_and_b64 vcc, exec, s[8:9]
	v_mov_b64_e32 v[6:7], s[30:31]
	s_waitcnt lgkmcnt(3)
	v_mfma_f32_16x16x32_bf16 v[16:19], v[220:223], v[36:39], 0
	v_mfma_f32_16x16x32_bf16 v[84:87], v[220:223], v[44:47], 0
	s_cbranch_vccnz .LBB0_734
	v_mfma_f32_16x16x32_bf16 v[4:7], v[220:223], v[0:3], 0
.LBB0_734:
	s_and_b64 vcc, exec, s[10:11]
	s_waitcnt lgkmcnt(2)
	v_mfma_f32_16x16x32_bf16 v[12:15], v[224:227], v[40:43], v[16:19]
	v_mfma_f32_16x16x32_bf16 v[16:19], v[224:227], v[48:51], v[84:87]
	s_cbranch_vccnz .LBB0_736
	v_mfma_f32_16x16x32_bf16 v[4:7], v[224:227], v[0:3], v[4:7]
.LBB0_736:
	s_nop 0
	s_and_b64 vcc, exec, s[12:13]
	s_waitcnt lgkmcnt(1)
	v_mfma_f32_16x16x32_bf16 v[12:15], v[228:231], v[52:55], v[12:15]
	v_mfma_f32_16x16x32_bf16 v[84:87], v[228:231], v[60:63], v[16:19]
	s_cbranch_vccnz .LBB0_738
	v_mfma_f32_16x16x32_bf16 v[4:7], v[228:231], v[0:3], v[4:7]
.LBB0_738:
	s_nop 0
	s_and_b64 vcc, exec, s[14:15]
	s_waitcnt lgkmcnt(0)
	v_mfma_f32_16x16x32_bf16 v[16:19], v[232:235], v[56:59], v[12:15]
	v_mfma_f32_16x16x32_bf16 v[12:15], v[232:235], v[64:67], v[84:87]
	s_cbranch_vccnz .LBB0_740
	v_mfma_f32_16x16x32_bf16 v[4:7], v[232:235], v[0:3], v[4:7]

; #define LAS __attribute__((address_space(3)))
; template <bool PASS2>
; __device__ __forceinline__ void lru_item(const Frame& F, const Args& a, int item) {
;     ...
;             f32x4 ar[4], ai[4], ax[4];
; #pragma unroll
;             for (int rt = 0; rt < 4; ++rt) { ar[rt] = (f32x4){0.f, 0.f, 0.f, 0.f}; ai[rt] = (f32x4){0.f, 0.f, 0.f, 0.f}; ax[rt] = (f32x4){0.f, 0.f, 0.f, 0.f};
; #pragma unroll
;                 for (int ks = 0; ks < 4; ++ks) { const bf16x8 xf = *(const LAS bf16x8*)(AT + (64 * s + 16 * rt + fr) * AT_PITCH + 64 * ks + 16 * fq);
;                     ar[rt] = __builtin_amdgcn_mfma_f32_16x16x32_bf16(xf, wrf[ks], ar[rt], 0, 0, 0); ai[rt] = __builtin_amdgcn_mfma_f32_16x16x32_bf16(xf, wif[ks], ai[rt], 0, 0, 0);
;                     if (ks == ks0) ax[rt] = __builtin_amdgcn_mfma_f32_16x16x32_bf16(xf, sel, ax[rt], 0, 0, 0); } }
.LBB0_746:
	v_bitop3_b32 v36, s2, v95, v141 bitop3:0xde
	v_mul_lo_u32 v36, v36, s50
	v_add_u32_e32 v206, v107, v36
	ds_read_b128 v[212:215], v206
	ds_read_b128 v[216:219], v206 offset:64
	ds_read_b128 v[220:223], v206 offset:128
	ds_read_b128 v[224:227], v206 offset:192
	ds_read_b128 v[228:231], v206 offset:4352
	ds_read_b128 v[232:235], v206 offset:4416
	ds_read_b128 v[236:239], v206 offset:4480
	ds_read_b128 v[244:247], v206 offset:4544
	ds_read_b128 v[248:251], v206 offset:8704
	ds_read_b128 v[252:255], v206 offset:8768
	s_mov_b32 s30, s28
	s_mov_b32 s31, s28
	s_mov_b32 s29, s28
	v_mov_b64_e32 v[38:39], s[30:31]
	s_and_b64 vcc, exec, s[8:9]
	v_mov_b64_e32 v[36:37], s[28:29]
	s_waitcnt lgkmcnt(9)
	v_mfma_f32_16x16x32_bf16 v[44:47], v[212:215], v[32:35], 0
	v_mfma_f32_16x16x32_bf16 v[48:51], v[212:215], v[20:23], 0
	s_cbranch_vccnz .LBB0_748
	v_mfma_f32_16x16x32_bf16 v[36:39], v[212:215], v[0:3], 0
.LBB0_748:
	ds_read_b128 v[212:215], v206 offset:8832
	s_and_b64 vcc, exec, s[10:11]
	s_waitcnt lgkmcnt(9)
	s_nop 0
	v_mfma_f32_16x16x32_bf16 v[40:43], v[216:219], v[4:7], v[44:47]
	v_mfma_f32_16x16x32_bf16 v[44:47], v[216:219], v[12:15], v[48:51]
	s_cbranch_vccnz .LBB0_750
	v_mfma_f32_16x16x32_bf16 v[36:39], v[216:219], v[0:3], v[36:39]
.LBB0_750:
	ds_read_b128 v[216:219], v206 offset:8896
	s_and_b64 vcc, exec, s[12:13]
	s_waitcnt lgkmcnt(9)
	v_mfma_f32_16x16x32_bf16 v[40:43], v[220:223], v[8:11], v[40:43]
	v_mfma_f32_16x16x32_bf16 v[48:51], v[220:223], v[16:19], v[44:47]
	s_cbranch_vccnz .LBB0_752
	v_mfma_f32_16x16x32_bf16 v[36:39], v[220:223], v[0:3], v[36:39]
.LBB0_752:
	ds_read_b128 v[220:223], v206 offset:13056
	s_and_b64 vcc, exec, s[14:15]
	s_waitcnt lgkmcnt(9)
	v_mfma_f32_16x16x32_bf16 v[44:47], v[224:227], v[24:27], v[40:43]
	v_mfma_f32_16x16x32_bf16 v[40:43], v[224:227], v[28:31], v[48:51]
	s_cbranch_vccnz .LBB0_754
	v_mfma_f32_16x16x32_bf16 v[36:39], v[224:227], v[0:3], v[36:39]
.LBB0_754:
	ds_read_b128 v[224:227], v206 offset:13120
	s_mov_b32 s30, s28
	s_mov_b32 s31, s28
	s_mov_b32 s29, s28
	v_mov_b64_e32 v[50:51], s[30:31]
	s_and_b64 vcc, exec, s[8:9]
	v_mov_b64_e32 v[48:49], s[28:29]
	s_waitcnt lgkmcnt(9)
	v_mfma_f32_16x16x32_bf16 v[56:59], v[228:231], v[32:35], 0
	v_mfma_f32_16x16x32_bf16 v[60:63], v[228:231], v[20:23], 0
	s_cbranch_vccnz .LBB0_756
	v_mfma_f32_16x16x32_bf16 v[48:51], v[228:231], v[0:3], 0
.LBB0_756:
	ds_read_b128 v[228:231], v206 offset:13184
	s_and_b64 vcc, exec, s[10:11]
	s_waitcnt lgkmcnt(9)
	s_nop 0
	v_mfma_f32_16x16x32_bf16 v[52:55], v[232:235], v[4:7], v[56:59]
	v_mfma_f32_16x16x32_bf16 v[56:59], v[232:235], v[12:15], v[60:63]
	s_cbranch_vccnz .LBB0_758
	v_mfma_f32_16x16x32_bf16 v[48:51], v[232:235], v[0:3], v[48:51]
.LBB0_758:
	ds_read_b128 v[232:235], v206 offset:13248
	s_and_b64 vcc, exec, s[12:13]
	s_waitcnt lgkmcnt(9)
	v_mfma_f32_16x16x32_bf16 v[52:55], v[236:239], v[8:11], v[52:55]
	v_mfma_f32_16x16x32_bf16 v[60:63], v[236:239], v[16:19], v[56:59]
	s_cbranch_vccnz .LBB0_760
	v_mfma_f32_16x16x32_bf16 v[48:51], v[236:239], v[0:3], v[48:51]
.LBB0_760:
	s_and_b64 vcc, exec, s[14:15]
	s_waitcnt lgkmcnt(8)
	v_mfma_f32_16x16x32_bf16 v[56:59], v[244:247], v[24:27], v[52:55]
	v_mfma_f32_16x16x32_bf16 v[52:55], v[244:247], v[28:31], v[60:63]
	s_cbranch_vccnz .LBB0_762
	v_mfma_f32_16x16x32_bf16 v[48:51], v[244:247], v[0:3], v[48:51]
.LBB0_762:
	s_mov_b32 s30, s28
	s_mov_b32 s31, s28
	s_mov_b32 s29, s28
	v_mov_b64_e32 v[62:63], s[30:31]
	s_and_b64 vcc, exec, s[8:9]
	v_mov_b64_e32 v[60:61], s[28:29]
	s_waitcnt lgkmcnt(7)
	v_mfma_f32_16x16x32_bf16 v[68:71], v[248:251], v[32:35], 0
	v_mfma_f32_16x16x32_bf16 v[72:75], v[248:251], v[20:23], 0
	s_cbranch_vccnz .LBB0_764
	v_mfma_f32_16x16x32_bf16 v[60:63], v[248:251], v[0:3], 0
.LBB0_764:
	s_and_b64 vcc, exec, s[10:11]
	s_waitcnt lgkmcnt(6)
	s_nop 0
	v_mfma_f32_16x16x32_bf16 v[64:67], v[252:255], v[4:7], v[68:71]
	v_mfma_f32_16x16x32_bf16 v[68:71], v[252:255], v[12:15], v[72:75]
	s_cbranch_vccnz .LBB0_766
	v_mfma_f32_16x16x32_bf16 v[60:63], v[252:255], v[0:3], v[60:63]
.LBB0_766:
	s_and_b64 vcc, exec, s[12:13]
	s_waitcnt lgkmcnt(5)
	v_mfma_f32_16x16x32_bf16 v[64:67], v[212:215], v[8:11], v[64:67]
	v_mfma_f32_16x16x32_bf16 v[72:75], v[212:215], v[16:19], v[68:71]
	s_cbranch_vccnz .LBB0_768
	v_mfma_f32_16x16x32_bf16 v[60:63], v[212:215], v[0:3], v[60:63]
.LBB0_768:
	s_and_b64 vcc, exec, s[14:15]
	s_waitcnt lgkmcnt(4)
	v_mfma_f32_16x16x32_bf16 v[68:71], v[216:219], v[24:27], v[64:67]
	v_mfma_f32_16x16x32_bf16 v[64:67], v[216:219], v[28:31], v[72:75]
	s_cbranch_vccnz .LBB0_770
	v_mfma_f32_16x16x32_bf16 v[60:63], v[216:219], v[0:3], v[60:63]
.LBB0_770:
	s_mov_b32 s30, s28
	s_mov_b32 s31, s28
	s_mov_b32 s29, s28
	v_mov_b64_e32 v[74:75], s[30:31]
	s_and_b64 vcc, exec, s[8:9]
	v_mov_b64_e32 v[72:73], s[28:29]
	s_waitcnt lgkmcnt(3)
	v_mfma_f32_16x16x32_bf16 v[80:83], v[220:223], v[32:35], 0
	v_mfma_f32_16x16x32_bf16 v[84:87], v[220:223], v[20:23], 0
	s_cbranch_vccnz .LBB0_772
	v_mfma_f32_16x16x32_bf16 v[72:75], v[220:223], v[0:3], 0
.LBB0_772:
	s_and_b64 vcc, exec, s[10:11]
	s_waitcnt lgkmcnt(2)
	s_nop 0
	v_mfma_f32_16x16x32_bf16 v[76:79], v[224:227], v[4:7], v[80:83]
	v_mfma_f32_16x16x32_bf16 v[80:83], v[224:227], v[12:15], v[84:87]
	s_cbranch_vccnz .LBB0_774
	v_mfma_f32_16x16x32_bf16 v[72:75], v[224:227], v[0:3], v[72:75]
.LBB0_774:
	s_and_b64 vcc, exec, s[12:13]
	s_waitcnt lgkmcnt(1)
	v_mfma_f32_16x16x32_bf16 v[76:79], v[228:231], v[8:11], v[76:79]
	v_mfma_f32_16x16x32_bf16 v[84:87], v[228:231], v[16:19], v[80:83]
	s_cbranch_vccnz .LBB0_776
	v_mfma_f32_16x16x32_bf16 v[72:75], v[228:231], v[0:3], v[72:75]
.LBB0_776:
	s_and_b64 vcc, exec, s[14:15]
	s_waitcnt lgkmcnt(0)
	v_mfma_f32_16x16x32_bf16 v[80:83], v[232:235], v[24:27], v[76:79]
	v_mfma_f32_16x16x32_bf16 v[76:79], v[232:235], v[28:31], v[84:87]
	s_cbranch_vccnz .LBB0_745
	v_mfma_f32_16x16x32_bf16 v[72:75], v[232:235], v[0:3], v[72:75]
	s_branch .LBB0_745

; #define LAS __attribute__((address_space(3)))
; template <bool PASS2>
; __device__ __forceinline__ void lru_item(const Frame& F, const Args& a, int item) {
;     ...
;             f32x4 ar[4], ai[4], ax[4];
; #pragma unroll
;             for (int rt = 0; rt < 4; ++rt) { ar[rt] = (f32x4){0.f, 0.f, 0.f, 0.f}; ai[rt] = (f32x4){0.f, 0.f, 0.f, 0.f}; ax[rt] = (f32x4){0.f, 0.f, 0.f, 0.f};
; #pragma unroll
;                 for (int ks = 0; ks < 4; ++ks) { const bf16x8 xf = *(const LAS bf16x8*)(AT + (64 * s + 16 * rt + fr) * AT_PITCH + 64 * ks + 16 * fq);
;                     ar[rt] = __builtin_amdgcn_mfma_f32_16x16x32_bf16(xf, wrf[ks], ar[rt], 0, 0, 0); ai[rt] = __builtin_amdgcn_mfma_f32_16x16x32_bf16(xf, wif[ks], ai[rt], 0, 0, 0);
;                     if (ks == ks0) ax[rt] = __builtin_amdgcn_mfma_f32_16x16x32_bf16(xf, sel, ax[rt], 0, 0, 0); } }
.LBB0_827:
	v_add_u32_e32 v125, v209, v103
	v_add_u32_e32 v240, 0x11400, v125
	ds_read_b128 v[212:215], v240
	ds_read_b128 v[216:219], v240 offset:64
	ds_read_b128 v[220:223], v240 offset:128
	ds_read_b128 v[224:227], v240 offset:192
	ds_read_b128 v[228:231], v240 offset:4352
	ds_read_b128 v[232:235], v240 offset:4416
	ds_read_b128 v[236:239], v240 offset:4480
	ds_read_b128 v[244:247], v240 offset:4544
	ds_read_b128 v[248:251], v240 offset:8704
	ds_read_b128 v[252:255], v240 offset:8768
	v_mov_b32_e32 v182, v36
	v_mov_b32_e32 v179, v39
	v_mov_b32_e32 v180, v38
	v_mov_b32_e32 v181, v37
	v_mov_b32_e32 v174, v44
	v_cndmask_b32_e64 v44, 0, 1, s[2:3]
	v_mov_b32_e32 v173, v45
	v_mov_b32_e32 v175, v43
	v_mov_b32_e32 v176, v42
	v_mov_b32_e32 v177, v41
	v_mov_b32_e32 v178, v40
	s_waitcnt lgkmcnt(9)
	v_mfma_f32_16x16x32_bf16 v[40:43], v[212:215], v[4:7], 0
	v_cmp_ne_u32_e64 s[8:9], 1, v44
	s_mov_b32 s30, s28
	s_mov_b32 s31, s28
	v_mfma_f32_16x16x32_bf16 v[44:47], v[212:215], v[12:15], 0
	s_mov_b32 s29, s28
	v_mov_b64_e32 v[62:63], s[30:31]
	v_mov_b32_e32 v183, v132
	v_mov_b32_e32 v184, v131
	v_mov_b32_e32 v185, v146
	v_mov_b32_e32 v186, v143
	v_mov_b32_e32 v187, v142
	v_mov_b32_e32 v188, v133
	v_mov_b32_e32 v132, v198
	v_mov_b32_e32 v131, v200
	v_mov_b32_e32 v146, v202
	v_mov_b32_e32 v143, v203
	v_mov_b32_e32 v142, v205
	v_mov_b32_e32 v133, v124
	v_mov_b64_e32 v[60:61], s[28:29]
	s_andn2_b64 vcc, exec, s[2:3]
	s_cbranch_vccnz .LBB0_829
	v_mfma_f32_16x16x32_bf16 v[60:63], v[212:215], v[0:3], 0
.LBB0_829:
	ds_read_b128 v[212:215], v240 offset:8832
	s_andn2_b64 vcc, exec, s[36:37]
	s_waitcnt lgkmcnt(9)
	v_mfma_f32_16x16x32_bf16 v[36:39], v[216:219], v[8:11], v[40:43]
	s_nop 2
	v_cndmask_b32_e64 v40, 0, 1, s[36:37]
	v_cmp_ne_u32_e64 s[10:11], 1, v40
	v_mfma_f32_16x16x32_bf16 v[40:43], v[216:219], v[16:19], v[44:47]
	s_cbranch_vccnz .LBB0_831
	v_mfma_f32_16x16x32_bf16 v[60:63], v[216:219], v[0:3], v[60:63]
.LBB0_831:
	s_nop 0
	ds_read_b128 v[216:219], v240 offset:8896
	v_cndmask_b32_e64 v48, 0, 1, s[38:39]
	v_cmp_ne_u32_e64 s[12:13], 1, v48
	s_andn2_b64 vcc, exec, s[38:39]
	s_waitcnt lgkmcnt(9)
	v_mfma_f32_16x16x32_bf16 v[36:39], v[220:223], v[20:23], v[36:39]
	v_mfma_f32_16x16x32_bf16 v[40:43], v[220:223], v[28:31], v[40:43]
	s_cbranch_vccnz .LBB0_833
	v_mfma_f32_16x16x32_bf16 v[60:63], v[220:223], v[0:3], v[60:63]
.LBB0_833:
	ds_read_b128 v[220:223], v240 offset:13056
	s_andn2_b64 vcc, exec, s[40:41]
	s_waitcnt lgkmcnt(9)
	v_mfma_f32_16x16x32_bf16 v[80:83], v[224:227], v[24:27], v[36:39]
	s_nop 2
	v_cndmask_b32_e64 v36, 0, 1, s[40:41]
	v_cmp_ne_u32_e64 s[14:15], 1, v36
	v_mfma_f32_16x16x32_bf16 v[76:79], v[224:227], v[32:35], v[40:43]
	s_cbranch_vccnz .LBB0_835
	v_mfma_f32_16x16x32_bf16 v[60:63], v[224:227], v[0:3], v[60:63]
.LBB0_835:
	ds_read_b128 v[224:227], v240 offset:13120
	s_mov_b32 s30, s28
	s_mov_b32 s31, s28
	s_mov_b32 s29, s28
	v_mov_b64_e32 v[54:55], s[30:31]
	s_and_b64 vcc, exec, s[8:9]
	v_mov_b64_e32 v[52:53], s[28:29]
	s_waitcnt lgkmcnt(9)
	v_mfma_f32_16x16x32_bf16 v[40:43], v[228:231], v[4:7], 0
	v_mfma_f32_16x16x32_bf16 v[44:47], v[228:231], v[12:15], 0
	s_cbranch_vccnz .LBB0_837
	v_mfma_f32_16x16x32_bf16 v[52:55], v[228:231], v[0:3], 0
.LBB0_837:
	ds_read_b128 v[228:231], v240 offset:13184
	s_and_b64 vcc, exec, s[10:11]
	s_waitcnt lgkmcnt(9)
	v_mfma_f32_16x16x32_bf16 v[36:39], v[232:235], v[8:11], v[40:43]
	v_mfma_f32_16x16x32_bf16 v[40:43], v[232:235], v[16:19], v[44:47]
	s_cbranch_vccnz .LBB0_839
	v_mfma_f32_16x16x32_bf16 v[52:55], v[232:235], v[0:3], v[52:55]
.LBB0_839:
	s_nop 0
	ds_read_b128 v[232:235], v240 offset:13248
	s_and_b64 vcc, exec, s[12:13]
	s_waitcnt lgkmcnt(9)
	v_mfma_f32_16x16x32_bf16 v[36:39], v[236:239], v[20:23], v[36:39]
	v_mfma_f32_16x16x32_bf16 v[40:43], v[236:239], v[28:31], v[40:43]
	s_cbranch_vccnz .LBB0_841
	v_mfma_f32_16x16x32_bf16 v[52:55], v[236:239], v[0:3], v[52:55]
.LBB0_841:
	s_and_b64 vcc, exec, s[14:15]
	s_waitcnt lgkmcnt(8)
	v_mfma_f32_16x16x32_bf16 v[72:75], v[244:247], v[24:27], v[36:39]
	v_mfma_f32_16x16x32_bf16 v[68:71], v[244:247], v[32:35], v[40:43]
	s_cbranch_vccnz .LBB0_843
	v_mfma_f32_16x16x32_bf16 v[52:55], v[244:247], v[0:3], v[52:55]
.LBB0_843:
	s_mov_b32 s30, s28
	s_mov_b32 s31, s28
	s_mov_b32 s29, s28
	v_mov_b64_e32 v[42:43], s[30:31]
	s_and_b64 vcc, exec, s[8:9]
	v_mov_b64_e32 v[40:41], s[28:29]
	s_waitcnt lgkmcnt(7)
	v_mfma_f32_16x16x32_bf16 v[44:47], v[248:251], v[4:7], 0
	v_mfma_f32_16x16x32_bf16 v[48:51], v[248:251], v[12:15], 0
	s_cbranch_vccnz .LBB0_845
	v_mfma_f32_16x16x32_bf16 v[40:43], v[248:251], v[0:3], 0
.LBB0_845:
	s_and_b64 vcc, exec, s[10:11]
	s_waitcnt lgkmcnt(6)
	v_mfma_f32_16x16x32_bf16 v[36:39], v[252:255], v[8:11], v[44:47]
	v_mfma_f32_16x16x32_bf16 v[44:47], v[252:255], v[16:19], v[48:51]
	s_cbranch_vccnz .LBB0_847
	v_mfma_f32_16x16x32_bf16 v[40:43], v[252:255], v[0:3], v[40:43]
.LBB0_847:
	s_nop 0
	s_and_b64 vcc, exec, s[12:13]
	s_waitcnt lgkmcnt(5)
	v_mfma_f32_16x16x32_bf16 v[36:39], v[212:215], v[20:23], v[36:39]
	v_mfma_f32_16x16x32_bf16 v[44:47], v[212:215], v[28:31], v[44:47]
	s_cbranch_vccnz .LBB0_849
	v_mfma_f32_16x16x32_bf16 v[40:43], v[212:215], v[0:3], v[40:43]
.LBB0_849:
	s_and_b64 vcc, exec, s[14:15]
	s_waitcnt lgkmcnt(4)
	v_mfma_f32_16x16x32_bf16 v[64:67], v[216:219], v[24:27], v[36:39]
	v_mfma_f32_16x16x32_bf16 v[56:59], v[216:219], v[32:35], v[44:47]
	s_cbranch_vccnz .LBB0_851
	v_mfma_f32_16x16x32_bf16 v[40:43], v[216:219], v[0:3], v[40:43]
.LBB0_851:
	s_mov_b32 s30, s28
	s_mov_b32 s31, s28
	s_mov_b32 s29, s28
	v_mov_b64_e32 v[38:39], s[30:31]
	s_and_b64 vcc, exec, s[8:9]
	v_mov_b64_e32 v[36:37], s[28:29]
	s_waitcnt lgkmcnt(3)
	v_mfma_f32_16x16x32_bf16 v[48:51], v[220:223], v[4:7], 0
	v_mfma_f32_16x16x32_bf16 v[84:87], v[220:223], v[12:15], 0
	s_cbranch_vccnz .LBB0_853
	v_mfma_f32_16x16x32_bf16 v[36:39], v[220:223], v[0:3], 0
.LBB0_853:
	s_and_b64 vcc, exec, s[10:11]
	s_waitcnt lgkmcnt(2)
	v_mfma_f32_16x16x32_bf16 v[44:47], v[224:227], v[8:11], v[48:51]
	v_mfma_f32_16x16x32_bf16 v[48:51], v[224:227], v[16:19], v[84:87]
	s_cbranch_vccnz .LBB0_855
	v_mfma_f32_16x16x32_bf16 v[36:39], v[224:227], v[0:3], v[36:39]
.LBB0_855:
	s_nop 0
	s_and_b64 vcc, exec, s[12:13]
	s_waitcnt lgkmcnt(1)
	v_mfma_f32_16x16x32_bf16 v[44:47], v[228:231], v[20:23], v[44:47]
	v_mfma_f32_16x16x32_bf16 v[84:87], v[228:231], v[28:31], v[48:51]
	s_cbranch_vccnz .LBB0_857
	v_mfma_f32_16x16x32_bf16 v[36:39], v[228:231], v[0:3], v[36:39]
.LBB0_857:
	s_nop 0
	s_and_b64 vcc, exec, s[14:15]
	s_waitcnt lgkmcnt(0)
	v_mfma_f32_16x16x32_bf16 v[48:51], v[232:235], v[24:27], v[44:47]
	v_mfma_f32_16x16x32_bf16 v[44:47], v[232:235], v[32:35], v[84:87]
	s_cbranch_vccnz .LBB0_859
	v_mfma_f32_16x16x32_bf16 v[36:39], v[232:235], v[0:3], v[36:39]

; #define LAS __attribute__((address_space(3)))
; template <bool PASS2>
; __device__ __forceinline__ void lru_item(const Frame& F, const Args& a, int item) {
;     ...
;             f32x4 ar[4], ai[4], ax[4];
; #pragma unroll
;             for (int rt = 0; rt < 4; ++rt) { ar[rt] = (f32x4){0.f, 0.f, 0.f, 0.f}; ai[rt] = (f32x4){0.f, 0.f, 0.f, 0.f}; ax[rt] = (f32x4){0.f, 0.f, 0.f, 0.f};
; #pragma unroll
;                 for (int ks = 0; ks < 4; ++ks) { const bf16x8 xf = *(const LAS bf16x8*)(AT + (64 * s + 16 * rt + fr) * AT_PITCH + 64 * ks + 16 * fq);
;                     ar[rt] = __builtin_amdgcn_mfma_f32_16x16x32_bf16(xf, wrf[ks], ar[rt], 0, 0, 0); ai[rt] = __builtin_amdgcn_mfma_f32_16x16x32_bf16(xf, wif[ks], ai[rt], 0, 0, 0);
;                     if (ks == ks0) ax[rt] = __builtin_amdgcn_mfma_f32_16x16x32_bf16(xf, sel, ax[rt], 0, 0, 0); } }
.LBB0_865:
	v_bitop3_b32 v36, s46, v145, v140 bitop3:0xde
	v_mul_lo_u32 v36, v36, s33
	v_add_u32_e32 v206, v105, v36
	ds_read_b128 v[212:215], v206
	ds_read_b128 v[216:219], v206 offset:64
	ds_read_b128 v[220:223], v206 offset:128
	ds_read_b128 v[224:227], v206 offset:192
	ds_read_b128 v[228:231], v206 offset:4352
	ds_read_b128 v[232:235], v206 offset:4416
	ds_read_b128 v[236:239], v206 offset:4480
	ds_read_b128 v[244:247], v206 offset:4544
	ds_read_b128 v[248:251], v206 offset:8704
	ds_read_b128 v[252:255], v206 offset:8768
	s_mov_b32 s30, s28
	s_mov_b32 s31, s28
	s_mov_b32 s29, s28
	v_mov_b64_e32 v[38:39], s[30:31]
	s_and_b64 vcc, exec, s[8:9]
	v_mov_b64_e32 v[36:37], s[28:29]
	s_waitcnt lgkmcnt(9)
	v_mfma_f32_16x16x32_bf16 v[44:47], v[212:215], v[32:35], 0
	v_mfma_f32_16x16x32_bf16 v[48:51], v[212:215], v[20:23], 0
	s_cbranch_vccnz .LBB0_867
	v_mfma_f32_16x16x32_bf16 v[36:39], v[212:215], v[0:3], 0
